# v1 + attention LDS-DMA pieces: no m0 save/restore, s_nop 0 pad
# speedup vs baseline: 1.0099x; 1.0099x over previous
.LBB0_826:
	s_cmp_lg_u32 s0, 0
	v_mbcnt_lo_u32_b32 v204, -1, 0
	v_mbcnt_hi_u32_b32 v204, -1, v204
	s_nop 0
	v_lshlrev_b32_e32 v216, 4, v204
	s_cbranch_scc1 .LBB0_828
	s_mov_b32 m0, s78
	s_nop 0
	global_load_lds_dwordx4 v216, s[14:15]
	s_nop 0
	s_mov_b32 m0, s85
	s_nop 0
	global_load_lds_dwordx4 v216, s[16:17]
.LBB0_828:
	s_lshr_b32 s1, s0, 1
	s_or_b32 s1, s1, s3
	s_and_b32 s4, s0, 1
	s_sub_i32 s6, 15, s1
	s_cmp_eq_u32 s4, 0
	s_cselect_b64 s[56:57], -1, 0
	s_and_b64 s[4:5], s[56:57], exec
	s_cselect_b32 s1, s1, s6
	s_lshl_b32 s13, s1, 8
	s_add_u32 s54, s75, s13
	s_addc_u32 s55, s79, 0
	s_mul_i32 s4, s55, 0x600
	s_mul_hi_u32 s5, s54, 0x600
	v_ashrrev_i32_e32 v206, 5, v204
	s_add_i32 s5, s5, s4
	s_mul_i32 s4, s54, 0x600
	v_readfirstlane_b32 s6, v200
	v_and_b32_e32 v205, 31, v204
	s_add_u32 s4, s81, s4
	s_mov_b32 m0, s6
	s_nop 0
	global_load_lds_dwordx4 v216, s[18:19]
	v_readfirstlane_b32 s6, v201
	v_lshlrev_b32_e32 v2, 3, v206
	s_addc_u32 s5, s82, s5
	s_add_i32 s7, s6, s91
	v_mul_u32_u24_e32 v0, 0x300, v205
	v_ashrrev_i32_e32 v3, 31, v2
	s_mov_b32 m0, s7
	s_nop 0
	global_load_lds_dwordx4 v216, s[20:21]
	v_readfirstlane_b32 s7, v202
	v_lshl_add_u64 v[2:3], v[2:3], 1, s[4:5]
	v_lshlrev_b32_e32 v0, 1, v0
	s_add_i32 s10, s7, s91
	s_mov_b32 m0, s10
	s_nop 0
	global_load_lds_dwordx4 v216, s[30:31]
	v_lshl_add_u64 v[2:3], v[2:3], 0, v[0:1]
	global_load_dwordx4 v[176:179], v[2:3], off
	global_load_dwordx4 v[168:171], v[2:3], off offset:32
	global_load_dwordx4 v[164:167], v[2:3], off offset:64
	s_waitcnt lgkmcnt(0)
	global_load_dwordx4 v[156:159], v[2:3], off offset:96
	global_load_dwordx4 v[148:151], v[2:3], off offset:128
	global_load_dwordx4 v[144:147], v[2:3], off offset:160
	v_mov_b64_e32 v[46:47], v[30:31]
	v_mov_b64_e32 v[44:45], v[28:29]
	v_mov_b64_e32 v[42:43], v[26:27]
	v_mov_b64_e32 v[40:41], v[24:25]
	v_mov_b64_e32 v[38:39], v[22:23]
	v_mov_b64_e32 v[36:37], v[20:21]
	v_mov_b64_e32 v[34:35], v[18:19]
	v_mov_b64_e32 v[32:33], v[16:17]
	s_add_i32 s6, s6, s92
	s_mov_b32 m0, s6
	s_nop 0
	global_load_lds_dwordx4 v216, s[34:35]
	v_lshlrev_b32_e32 v0, 10, v206
	v_lshlrev_b32_e32 v4, 4, v205
	s_add_i32 s7, s7, s92
	s_mov_b32 m0, s7
	s_nop 0
	global_load_lds_dwordx4 v216, s[36:37]
	v_add3_u32 v214, 0, v0, v4
	s_waitcnt vmcnt(5) lgkmcnt(0)
	s_barrier
	ds_read_b128 v[2:5], v214
	ds_read_b128 v[6:9], v214 offset:512
	s_cmp_lg_u32 s1, 0
	s_cselect_b64 s[4:5], -1, 0
	v_lshlrev_b32_e32 v212, 2, v206
	v_or_b32_e32 v213, s74, v205
	s_and_b64 vcc, exec, s[4:5]
	s_waitcnt vmcnt(5) lgkmcnt(1)
	v_mfma_f32_32x32x16_bf16 v[48:63], v[2:5], v[176:179], v[32:47]
	s_waitcnt lgkmcnt(0)
	v_mfma_f32_32x32x16_bf16 v[32:47], v[6:9], v[176:179], v[32:47]
	ds_read_b128 v[2:5], v214 offset:2048
	ds_read_b128 v[6:9], v214 offset:2560
	s_waitcnt vmcnt(4) lgkmcnt(1)
	v_mfma_f32_32x32x16_bf16 v[48:63], v[2:5], v[168:171], v[48:63]
	s_waitcnt lgkmcnt(0)
	v_mfma_f32_32x32x16_bf16 v[32:47], v[6:9], v[168:171], v[32:47]
	ds_read_b128 v[2:5], v214 offset:4096
	ds_read_b128 v[6:9], v214 offset:4608
	s_waitcnt vmcnt(3) lgkmcnt(1)
	v_mfma_f32_32x32x16_bf16 v[48:63], v[2:5], v[164:167], v[48:63]
	s_waitcnt lgkmcnt(0)
	v_mfma_f32_32x32x16_bf16 v[32:47], v[6:9], v[164:167], v[32:47]
	ds_read_b128 v[2:5], v214 offset:6144
	ds_read_b128 v[6:9], v214 offset:6656
	s_waitcnt vmcnt(2) lgkmcnt(1)
	v_mfma_f32_32x32x16_bf16 v[48:63], v[2:5], v[156:159], v[48:63]
	s_waitcnt lgkmcnt(0)
	v_mfma_f32_32x32x16_bf16 v[32:47], v[6:9], v[156:159], v[32:47]
	ds_read_b128 v[2:5], v214 offset:8192
	ds_read_b128 v[6:9], v214 offset:8704
	s_waitcnt vmcnt(1) lgkmcnt(1)
	v_mfma_f32_32x32x16_bf16 v[48:63], v[2:5], v[148:151], v[48:63]
	s_waitcnt lgkmcnt(0)
	v_mfma_f32_32x32x16_bf16 v[32:47], v[6:9], v[148:151], v[32:47]
	ds_read_b128 v[2:5], v214 offset:10240
	ds_read_b128 v[6:9], v214 offset:10752
	s_waitcnt vmcnt(0) lgkmcnt(1)
	v_mfma_f32_32x32x16_bf16 v[48:63], v[2:5], v[144:147], v[48:63]
	s_waitcnt lgkmcnt(0)
	v_mfma_f32_32x32x16_bf16 v[32:47], v[6:9], v[144:147], v[32:47]
	s_nop 15
	s_nop 7
	s_cbranch_vccnz .LBB0_830
	v_subrev_u32_e32 v0, s13, v212
	v_add_u32_e32 v2, 32, v0
	v_cmp_le_i32_e32 vcc, v2, v213
	v_add_u32_e32 v2, 33, v0
	s_nop 6
	v_cndmask_b32_e32 v32, v203, v32, vcc
	v_cmp_lt_i32_e32 vcc, v0, v213
	s_nop 1
	v_cndmask_b32_e32 v49, v203, v49, vcc
	v_cmp_le_i32_e32 vcc, v0, v213
	s_nop 1
	v_cndmask_b32_e32 v48, v203, v48, vcc
	v_cmp_le_i32_e32 vcc, v2, v213
	v_or_b32_e32 v2, 2, v212
	s_nop 0
	v_cndmask_b32_e32 v33, v203, v33, vcc
	v_cmp_le_i32_e32 vcc, v2, v213
	v_add_u32_e32 v2, 34, v0
	s_nop 0
	v_cndmask_b32_e32 v50, v203, v50, vcc
	v_cmp_le_i32_e32 vcc, v2, v213
	v_or_b32_e32 v2, 3, v212
	s_nop 0
	v_cndmask_b32_e32 v34, v203, v34, vcc
	v_cmp_le_i32_e32 vcc, v2, v213
	v_add_u32_e32 v2, 35, v0
	s_nop 0
	v_cndmask_b32_e32 v51, v203, v51, vcc
	v_cmp_le_i32_e32 vcc, v2, v213
	v_add_u32_e32 v2, 8, v0
	s_nop 0
	v_cndmask_b32_e32 v35, v203, v35, vcc
	v_cmp_le_i32_e32 vcc, v2, v213
	v_add_u32_e32 v2, 40, v0
	s_nop 0
	v_cndmask_b32_e32 v52, v203, v52, vcc
	v_cmp_le_i32_e32 vcc, v2, v213
	v_add_u32_e32 v2, 9, v0
	s_nop 0
	v_cndmask_b32_e32 v36, v203, v36, vcc
	v_cmp_le_i32_e32 vcc, v2, v213
	v_add_u32_e32 v2, 41, v0
	s_nop 0
	v_cndmask_b32_e32 v53, v203, v53, vcc
	v_cmp_le_i32_e32 vcc, v2, v213
	v_add_u32_e32 v2, 10, v0
	s_nop 0
	v_cndmask_b32_e32 v37, v203, v37, vcc
	v_cmp_le_i32_e32 vcc, v2, v213
	v_add_u32_e32 v2, 42, v0
	s_nop 0
	v_cndmask_b32_e32 v54, v203, v54, vcc
	v_cmp_le_i32_e32 vcc, v2, v213
	v_add_u32_e32 v2, 11, v0
	s_nop 0
	v_cndmask_b32_e32 v38, v203, v38, vcc
	v_cmp_le_i32_e32 vcc, v2, v213
	v_add_u32_e32 v2, 43, v0
	s_nop 0
	v_cndmask_b32_e32 v55, v203, v55, vcc
	v_cmp_le_i32_e32 vcc, v2, v213
	v_add_u32_e32 v2, 16, v0
	s_nop 0
	v_cndmask_b32_e32 v39, v203, v39, vcc
	v_cmp_le_i32_e32 vcc, v2, v213
	v_add_u32_e32 v2, 48, v0
	s_nop 0
	v_cndmask_b32_e32 v56, v203, v56, vcc
	v_cmp_le_i32_e32 vcc, v2, v213
	v_add_u32_e32 v2, 17, v0
	s_nop 0
	v_cndmask_b32_e32 v40, v203, v40, vcc
	v_cmp_le_i32_e32 vcc, v2, v213
	v_add_u32_e32 v2, 49, v0
	s_nop 0
	v_cndmask_b32_e32 v57, v203, v57, vcc
	v_cmp_le_i32_e32 vcc, v2, v213
	v_add_u32_e32 v2, 18, v0
	s_nop 0
	v_cndmask_b32_e32 v41, v203, v41, vcc
	v_cmp_le_i32_e32 vcc, v2, v213
	v_add_u32_e32 v2, 50, v0
	s_nop 0
	v_cndmask_b32_e32 v58, v203, v58, vcc
	v_cmp_le_i32_e32 vcc, v2, v213
	v_add_u32_e32 v2, 19, v0
	s_nop 0
	v_cndmask_b32_e32 v42, v203, v42, vcc
	v_cmp_le_i32_e32 vcc, v2, v213
	v_add_u32_e32 v2, 51, v0
	s_nop 0
	v_cndmask_b32_e32 v59, v203, v59, vcc
	v_cmp_le_i32_e32 vcc, v2, v213
	v_add_u32_e32 v2, 24, v0
	s_nop 0
	v_cndmask_b32_e32 v43, v203, v43, vcc
	v_cmp_le_i32_e32 vcc, v2, v213
	v_add_u32_e32 v2, 56, v0
	s_nop 0
	v_cndmask_b32_e32 v60, v203, v60, vcc
	v_cmp_le_i32_e32 vcc, v2, v213
	v_add_u32_e32 v2, 25, v0
	s_nop 0
	v_cndmask_b32_e32 v44, v203, v44, vcc
	v_cmp_le_i32_e32 vcc, v2, v213
	v_add_u32_e32 v2, 57, v0
	s_nop 0
	v_cndmask_b32_e32 v61, v203, v61, vcc
	v_cmp_le_i32_e32 vcc, v2, v213
	v_add_u32_e32 v2, 26, v0
	s_nop 0
	v_cndmask_b32_e32 v45, v203, v45, vcc
	v_cmp_le_i32_e32 vcc, v2, v213
	v_add_u32_e32 v2, 58, v0
	s_nop 0
	v_cndmask_b32_e32 v62, v203, v62, vcc
	v_cmp_le_i32_e32 vcc, v2, v213
	v_add_u32_e32 v2, 27, v0
	v_add_u32_e32 v0, 59, v0
	v_cndmask_b32_e32 v46, v203, v46, vcc
	v_cmp_le_i32_e32 vcc, v2, v213
	s_nop 1
	v_cndmask_b32_e32 v63, v203, v63, vcc
	v_cmp_le_i32_e32 vcc, v0, v213
	s_nop 1
	v_cndmask_b32_e32 v47, v203, v47, vcc
.LBB0_830:
	v_lshlrev_b32_e32 v0, 1, v204
	v_lshrrev_b32_e32 v2, 2, v204
	v_and_b32_e32 v209, 32, v0
	v_lshlrev_b32_e32 v211, 3, v204
	v_and_or_b32 v2, v2, 3, v212
	v_add_u32_e32 v0, 0, v209
	v_and_b32_e32 v210, 24, v211
	v_lshlrev_b32_e32 v208, 6, v2
	v_add3_u32 v217, v0, v210, v208
	v_max3_f32 v0, v48, v49, v32
	v_max3_f32 v2, v50, v51, v33
	s_add_i32 s6, s83, s93
	v_max3_f32 v0, v0, v34, v35
	v_max3_f32 v2, v2, v54, v55
	s_add_i32 s1, s13, 0x100
	v_max3_f32 v0, v0, v52, v53
	v_max3_f32 v2, v2, v38, v39
	s_lshr_b32 s1, s1, 6
	v_max3_f32 v0, v0, v36, v37
	v_max3_f32 v2, v2, v58, v59
	v_lshl_add_u32 v207, v212, 2, s87
	v_max3_f32 v0, v0, v56, v57
	v_max3_f32 v2, v2, v42, v43
	s_mov_b32 s10, 1
	v_max3_f32 v0, v0, v40, v41
	v_max3_f32 v2, v2, v62, v63
	s_mov_b32 s23, 0
	v_max3_f32 v0, v0, v60, v61
	v_max3_f32 v2, v2, v46, v47
	s_andn2_b64 vcc, exec, s[4:5]
	v_max3_f32 v0, v0, v44, v45
	v_cmp_gt_u32_e64 s[4:5], 32, v204
	v_max_f32_e32 v0, v0, v2
	s_nop 0
	v_mov_b32_e32 v2, v0
	s_nop 1
	v_permlane32_swap_b32_e32 v0, v2
	v_max_f32_e32 v0, v0, v2
	s_nop 0
	v_add_f32_e32 v215, v1, v0
	v_sub_f32_e32 v2, v48, v0
	v_sub_f32_e32 v3, v32, v0
	v_sub_f32_e32 v4, v49, v0
	v_sub_f32_e32 v5, v33, v0
	v_sub_f32_e32 v6, v50, v0
	s_nop 0
	v_xor_b32_e32 v64, 0x80000000, v215
	v_mov_b32_e32 v65, v64
	v_mov_b32_e32 v66, v64
	v_mov_b32_e32 v67, v64
	v_mov_b32_e32 v68, v64
	v_mov_b32_e32 v69, v64
	v_mov_b32_e32 v70, v64
	v_mov_b32_e32 v71, v64
	v_mov_b32_e32 v72, v64
	v_mov_b32_e32 v73, v64
	v_mov_b32_e32 v74, v64
	v_mov_b32_e32 v75, v64
	v_mov_b32_e32 v76, v64
	v_mov_b32_e32 v77, v64
	v_mov_b32_e32 v78, v64
	v_mov_b32_e32 v79, v64
	s_waitcnt vmcnt(0) lgkmcnt(0)
	s_barrier
	s_mov_b32 m0, s6
	s_nop 0
	global_load_lds_dwordx4 v216, s[38:39]
	s_add_i32 s6, s84, s93
	s_mov_b32 m0, s6
	s_nop 0
	global_load_lds_dwordx4 v216, s[40:41]
	s_add_i32 s6, s78, 0xe000
	s_mov_b32 m0, s6
	s_nop 0
	global_load_lds_dwordx4 v216, s[42:43]
	ds_read_b128 v[196:199], v214 offset:12288
	ds_read_b128 v[184:187], v214 offset:12800
	ds_read_b128 v[188:191], v214 offset:14336
	ds_read_b128 v[192:195], v214 offset:14848
	v_sub_f32_e32 v7, v34, v0
	v_sub_f32_e32 v8, v51, v0
	v_sub_f32_e32 v9, v35, v0
	v_sub_f32_e32 v10, v52, v0
	v_sub_f32_e32 v11, v36, v0
	v_sub_f32_e32 v12, v53, v0
	v_sub_f32_e32 v13, v37, v0
	v_sub_f32_e32 v14, v54, v0
	v_sub_f32_e32 v15, v38, v0
	v_sub_f32_e32 v32, v55, v0
	v_sub_f32_e32 v33, v39, v0
	v_sub_f32_e32 v34, v56, v0
	v_sub_f32_e32 v35, v40, v0
	v_sub_f32_e32 v36, v57, v0
	v_sub_f32_e32 v37, v41, v0
	v_sub_f32_e32 v38, v58, v0
	v_sub_f32_e32 v39, v42, v0
	v_sub_f32_e32 v40, v59, v0
	v_sub_f32_e32 v41, v43, v0
	v_sub_f32_e32 v42, v60, v0
	v_sub_f32_e32 v43, v44, v0
	v_sub_f32_e32 v44, v61, v0
	v_sub_f32_e32 v45, v45, v0
	v_sub_f32_e32 v48, v62, v0
	v_sub_f32_e32 v46, v46, v0
	v_sub_f32_e32 v49, v63, v0
	v_sub_f32_e32 v0, v47, v0
	v_exp_f32_e32 v96, v2
	v_exp_f32_e32 v97, v4
	v_exp_f32_e32 v98, v6
	v_exp_f32_e32 v99, v8
	v_exp_f32_e32 v100, v10
	v_exp_f32_e32 v101, v12
	v_exp_f32_e32 v102, v14
	v_exp_f32_e32 v103, v32
	v_exp_f32_e32 v104, v34
	v_exp_f32_e32 v105, v36
	v_exp_f32_e32 v106, v38
	v_exp_f32_e32 v107, v40
	v_exp_f32_e32 v108, v42
	v_exp_f32_e32 v109, v44
	v_exp_f32_e32 v110, v48
	v_exp_f32_e32 v111, v49
	v_exp_f32_e32 v80, v3
	v_exp_f32_e32 v81, v5
	v_exp_f32_e32 v82, v7
	v_exp_f32_e32 v83, v9
	v_exp_f32_e32 v84, v11
	v_exp_f32_e32 v85, v13
	v_exp_f32_e32 v86, v15
	v_exp_f32_e32 v87, v33
	v_exp_f32_e32 v88, v35
	v_exp_f32_e32 v89, v37
	v_exp_f32_e32 v90, v39
	v_exp_f32_e32 v91, v41
	v_exp_f32_e32 v92, v43
	v_exp_f32_e32 v93, v45
	v_exp_f32_e32 v94, v46
	v_exp_f32_e32 v95, v0
	s_cbranch_vccnz .LBB0_846
	v_mov_b32_e32 v14, v1
	v_mov_b32_e32 v15, v1
	v_mov_b32_e32 v0, v1
	v_mov_b32_e32 v2, v1
	v_mov_b32_e32 v3, v1
	v_mov_b32_e32 v4, v1
	v_mov_b32_e32 v5, v1
	v_mov_b32_e32 v6, v1
	v_mov_b32_e32 v7, v1
	v_mov_b32_e32 v8, v1
	v_mov_b32_e32 v9, v1
	v_mov_b32_e32 v10, v1
	v_mov_b32_e32 v11, v1
	v_mov_b32_e32 v12, v1
	v_mov_b32_e32 v13, v1
	v_mov_b64_e32 v[62:63], v[14:15]
	v_mov_b64_e32 v[46:47], v[14:15]
	s_add_i32 s66, s1, -5
	v_lshl_add_u32 v219, v205, 2, s87
	s_mov_b32 s62, 0
	s_movk_i32 s23, 0x4000
	s_movk_i32 s10, 0x2000
	v_mov_b32_e32 v218, 0
	s_mov_b32 s67, 4
	s_mov_b64 s[6:7], s[52:53]
	s_mov_b64 s[58:59], s[50:51]
	s_mov_b64 s[60:61], s[48:49]
	v_mov_b64_e32 v[60:61], v[12:13]
	v_mov_b64_e32 v[58:59], v[10:11]
	v_mov_b64_e32 v[56:57], v[8:9]
	v_mov_b64_e32 v[54:55], v[6:7]
	v_mov_b64_e32 v[52:53], v[4:5]
	v_mov_b64_e32 v[50:51], v[2:3]
	v_mov_b64_e32 v[48:49], v[0:1]
	v_mov_b64_e32 v[44:45], v[12:13]
	v_mov_b64_e32 v[42:43], v[10:11]
	v_mov_b64_e32 v[40:41], v[8:9]
	v_mov_b64_e32 v[38:39], v[6:7]
	v_mov_b64_e32 v[36:37], v[4:5]
	v_mov_b64_e32 v[34:35], v[2:3]
	v_mov_b64_e32 v[32:33], v[0:1]
.LBB0_832:
	v_cvt_pk_bf16_f32 v172, v104, v105
	v_cvt_pk_bf16_f32 v180, v96, v97
	s_add_i32 s12, s67, -3
	s_and_b32 s22, s12, 3
	s_mulk_i32 s22, 0x3000
	v_add_u32_e32 v0, s22, v214
	ds_read_b128 v[2:5], v0 offset:4096
	v_add_u32_e32 v14, s62, v217
	s_waitcnt lgkmcnt(4)
	v_mfma_f32_32x32x16_bf16 v[128:143], v[196:199], v[176:179], v[64:79]
	v_add_f32_e32 v6, v96, v97
	v_add_f32_e32 v6, v98, v6
	v_add_f32_e32 v6, v99, v6
	v_add_f32_e32 v10, v100, v6
	ds_read_b128 v[6:9], v0 offset:4608
	s_waitcnt lgkmcnt(4)
	v_mfma_f32_32x32x16_bf16 v[112:127], v[184:187], v[176:179], v[64:79]
	v_add_f32_e32 v10, v101, v10
	v_add_f32_e32 v10, v102, v10
	v_add_f32_e32 v15, v103, v10
	v_cvt_pk_bf16_f32 v181, v98, v99
	ds_read_b128 v[10:13], v0 offset:6144
	s_waitcnt lgkmcnt(4)
	v_mfma_f32_32x32x16_bf16 v[128:143], v[188:191], v[168:171], v[128:143]
	v_add_f32_e32 v15, v104, v15
	v_add_f32_e32 v15, v105, v15
	v_add_f32_e32 v15, v106, v15
	v_cvt_pk_bf16_f32 v182, v100, v101
	ds_read_b128 v[96:99], v0 offset:6656
	s_waitcnt lgkmcnt(4)
	v_mfma_f32_32x32x16_bf16 v[112:127], v[192:195], v[168:171], v[112:127]
	v_add_f32_e32 v15, v107, v15
	v_add_f32_e32 v15, v108, v15
	v_add_f32_e32 v15, v109, v15
	v_cvt_pk_bf16_f32 v183, v102, v103
	ds_read_b128 v[100:103], v0 offset:8192
	s_waitcnt lgkmcnt(4)
	v_mfma_f32_32x32x16_bf16 v[128:143], v[2:5], v[164:167], v[128:143]
	v_add_f32_e32 v15, v110, v15
	v_add_f32_e32 v15, v111, v15
	v_add_f32_e32 v15, v80, v15
	ds_read_b128 v[2:5], v0 offset:8704
	s_waitcnt lgkmcnt(4)
	v_mfma_f32_32x32x16_bf16 v[112:127], v[6:9], v[164:167], v[112:127]
	v_add_f32_e32 v15, v81, v15
	v_add_f32_e32 v15, v82, v15
	v_add_f32_e32 v15, v83, v15
	v_cvt_pk_bf16_f32 v173, v106, v107
	ds_read_b128 v[104:107], v0 offset:10240
	s_waitcnt lgkmcnt(4)
	v_mfma_f32_32x32x16_bf16 v[128:143], v[10:13], v[156:159], v[128:143]
	v_add_f32_e32 v6, v84, v15
	v_add_f32_e32 v6, v85, v6
	v_cvt_pk_bf16_f32 v174, v108, v109
	v_cvt_pk_bf16_f32 v175, v110, v111
	ds_read_b128 v[108:111], v0 offset:10752
	s_waitcnt lgkmcnt(4)
	v_mfma_f32_32x32x16_bf16 v[112:127], v[96:99], v[156:159], v[112:127]
	v_add_f32_e32 v0, v86, v6
	v_add_f32_e32 v0, v87, v0
	v_cvt_pk_bf16_f32 v160, v80, v81
	v_cvt_pk_bf16_f32 v161, v82, v83
	s_add_u32 s62, s58, 0xffff0000
	s_addc_u32 s63, s59, -1
	s_and_b32 s12, s67, 3
	s_mulk_i32 s12, 0x3000
	s_add_i32 s64, s12, s78
	s_mov_b32 m0, s64
	s_nop 0
	global_load_lds_dwordx4 v216, s[62:63]
	ds_read_b64_tr_b16 v[6:7], v14 offset:49152
	ds_read_b64_tr_b16 v[8:9], v14 offset:49664
	s_waitcnt lgkmcnt(5)
	v_mfma_f32_32x32x16_bf16 v[128:143], v[100:103], v[148:151], v[128:143]
	v_add_f32_e32 v0, v88, v0
	v_add_f32_e32 v0, v89, v0
	v_cvt_pk_bf16_f32 v162, v84, v85
	v_cvt_pk_bf16_f32 v163, v86, v87
	s_add_u32 s62, s60, 0xfffff000
	s_addc_u32 s63, s61, -1
	s_add_i32 s12, s12, s85
	s_mov_b32 m0, s12
	s_nop 0
	global_load_lds_dwordx4 v216, s[62:63]
	ds_read_b64_tr_b16 v[10:11], v14 offset:53248
	ds_read_b64_tr_b16 v[12:13], v14 offset:53760
	s_waitcnt lgkmcnt(6)
	v_mfma_f32_32x32x16_bf16 v[112:127], v[2:5], v[148:151], v[112:127]
	v_add_f32_e32 v0, v90, v0
	v_add_f32_e32 v0, v91, v0
	v_cvt_pk_bf16_f32 v152, v88, v89
	v_cvt_pk_bf16_f32 v153, v90, v91
	s_add_u32 s62, s6, 0xffff0000
	s_addc_u32 s63, s7, -1
	s_add_i32 s12, s23, s86
	s_mov_b32 m0, s12
	s_nop 0
	global_load_lds_dwordx4 v216, s[62:63]
	ds_read_b64_tr_b16 v[80:81], v14 offset:50176
	ds_read_b64_tr_b16 v[82:83], v14 offset:50688
	s_waitcnt lgkmcnt(7)
	v_mfma_f32_32x32x16_bf16 v[128:143], v[104:107], v[144:147], v[128:143]
	v_add_f32_e32 v0, v92, v0
	v_add_f32_e32 v0, v93, v0
	v_cvt_pk_bf16_f32 v154, v92, v93
	ds_read_b64_tr_b16 v[2:3], v14 offset:54272
	ds_read_b64_tr_b16 v[4:5], v14 offset:54784
	s_waitcnt lgkmcnt(8)
	v_mfma_f32_32x32x16_bf16 v[112:127], v[108:111], v[144:147], v[112:127]
	v_add_f32_e32 v0, v94, v0
	v_add_f32_e32 v0, v95, v0
	v_cvt_pk_bf16_f32 v155, v94, v95
	s_nop 1
	v_max_f32_e32 v15, v129, v129
	v_max_f32_e32 v84, v128, v128
	v_max_f32_e32 v15, v84, v15
	s_nop 3
	v_max3_f32 v84, v130, v131, v113
	v_max3_f32 v15, v15, v112, v114
	v_max3_f32 v15, v15, v115, v132
	v_max3_f32 v84, v84, v134, v135
	v_max3_f32 v15, v15, v133, v116
	v_max3_f32 v84, v84, v118, v119
	v_max3_f32 v15, v15, v117, v136
	v_max3_f32 v84, v84, v138, v139
	v_max3_f32 v15, v15, v137, v120
	v_max3_f32 v84, v84, v122, v123
	v_max3_f32 v15, v15, v121, v140
	v_max3_f32 v84, v84, v142, v143
	v_max3_f32 v15, v15, v141, v124
	v_max3_f32 v84, v84, v126, v127
	v_max3_f32 v15, v15, v125, v84
	v_mov_b32_e32 v84, v15
	s_nop 1
	v_permlane32_swap_b32_e32 v15, v84
	v_max_f32_e32 v84, v84, v84
	v_max_f32_e32 v15, v15, v15
	v_max_f32_e32 v15, v15, v84
	v_cmp_lt_f32_e32 vcc, s94, v15
	s_cmp_lg_u64 vcc, 0
	v_add_f32_e32 v0, v218, v0
	s_cselect_b64 s[62:63], -1, 0
	s_cbranch_vccnz .LBB0_840

.LBB0_835:
	s_add_i32 s12, s23, 0x2000
	s_cmpk_lg_i32 s23, 0x4000
	s_cselect_b32 s12, s12, 0
	ds_read_b128 v[188:191], v15 offset:4096
	v_add_u32_e32 v14, s10, v217
	s_waitcnt lgkmcnt(4)
	v_mfma_f32_32x32x16_bf16 v[96:111], v[2:5], v[176:179], v[64:79]
	v_add_f32_e32 v80, v128, v129
	v_add_f32_e32 v80, v130, v80
	v_add_f32_e32 v80, v131, v80
	v_add_f32_e32 v80, v132, v80
	v_cvt_pk_bf16_f32 v180, v128, v129
	ds_read_b128 v[2:5], v15 offset:4608
	v_add_f32_e32 v80, v133, v80
	v_add_f32_e32 v80, v134, v80
	v_add_f32_e32 v128, v135, v80
	s_waitcnt lgkmcnt(4)
	v_mfma_f32_32x32x16_bf16 v[80:95], v[6:9], v[176:179], v[64:79]
	v_cvt_pk_bf16_f32 v181, v130, v131
	ds_read_b128 v[6:9], v15 offset:6144
	s_waitcnt lgkmcnt(4)
	v_mfma_f32_32x32x16_bf16 v[96:111], v[10:13], v[168:171], v[96:111]
	v_add_f32_e32 v128, v136, v128
	v_add_f32_e32 v128, v137, v128
	v_add_f32_e32 v128, v138, v128
	v_cvt_pk_bf16_f32 v182, v132, v133
	ds_read_b128 v[10:13], v15 offset:6656
	s_waitcnt lgkmcnt(4)
	v_mfma_f32_32x32x16_bf16 v[80:95], v[184:187], v[168:171], v[80:95]
	v_add_f32_e32 v128, v139, v128
	v_add_f32_e32 v128, v140, v128
	v_add_f32_e32 v132, v141, v128
	v_cvt_pk_bf16_f32 v183, v134, v135
	ds_read_b128 v[128:131], v15 offset:8192
	s_waitcnt lgkmcnt(4)
	v_mfma_f32_32x32x16_bf16 v[96:111], v[188:191], v[164:167], v[96:111]
	v_add_f32_e32 v132, v142, v132
	v_add_f32_e32 v132, v143, v132
	v_add_f32_e32 v152, v112, v132
	v_cvt_pk_bf16_f32 v172, v136, v137
	ds_read_b128 v[132:135], v15 offset:8704
	s_waitcnt lgkmcnt(4)
	v_mfma_f32_32x32x16_bf16 v[80:95], v[2:5], v[164:167], v[80:95]
	v_add_f32_e32 v136, v113, v152
	v_add_f32_e32 v136, v114, v136
	v_add_f32_e32 v136, v115, v136
	v_cvt_pk_bf16_f32 v173, v138, v139
	ds_read_b128 v[2:5], v15 offset:10240
	s_waitcnt lgkmcnt(4)
	v_mfma_f32_32x32x16_bf16 v[96:111], v[6:9], v[156:159], v[96:111]
	v_add_f32_e32 v136, v116, v136
	v_add_f32_e32 v152, v117, v136
	v_cvt_pk_bf16_f32 v174, v140, v141
	v_cvt_pk_bf16_f32 v175, v142, v143
	ds_read_b128 v[136:139], v15 offset:10752
	s_waitcnt lgkmcnt(4)
	v_mfma_f32_32x32x16_bf16 v[80:95], v[10:13], v[156:159], v[80:95]
	v_add_f32_e32 v6, v118, v152
	v_add_f32_e32 v6, v119, v6
	v_cvt_pk_bf16_f32 v160, v112, v113
	v_cvt_pk_bf16_f32 v161, v114, v115
	s_add_i32 s10, s22, s78
	s_mov_b32 m0, s10
	s_nop 0
	global_load_lds_dwordx4 v216, s[58:59]
	ds_read_b64_tr_b16 v[112:113], v14 offset:49152
	ds_read_b64_tr_b16 v[114:115], v14 offset:49664
	s_waitcnt lgkmcnt(5)
	v_mfma_f32_32x32x16_bf16 v[96:111], v[128:131], v[148:151], v[96:111]
	v_add_f32_e32 v6, v120, v6
	v_add_f32_e32 v6, v121, v6
	v_cvt_pk_bf16_f32 v162, v116, v117
	v_cvt_pk_bf16_f32 v163, v118, v119
	s_add_i32 s10, s22, s85
	s_mov_b32 m0, s10
	s_nop 0
	global_load_lds_dwordx4 v216, s[60:61]
	ds_read_b64_tr_b16 v[10:11], v14 offset:53248
	ds_read_b64_tr_b16 v[12:13], v14 offset:53760
	s_waitcnt lgkmcnt(6)
	v_mfma_f32_32x32x16_bf16 v[80:95], v[132:135], v[148:151], v[80:95]
	v_add_f32_e32 v6, v122, v6
	v_add_f32_e32 v15, v123, v6
	v_cvt_pk_bf16_f32 v152, v120, v121
	v_cvt_pk_bf16_f32 v153, v122, v123
	s_add_i32 s10, s12, s86
	s_mov_b32 m0, s10
	s_nop 0
	global_load_lds_dwordx4 v216, s[6:7]
	ds_read_b64_tr_b16 v[6:7], v14 offset:50176
	ds_read_b64_tr_b16 v[8:9], v14 offset:50688
	s_waitcnt lgkmcnt(7)
	v_mfma_f32_32x32x16_bf16 v[96:111], v[2:5], v[144:147], v[96:111]
	v_add_f32_e32 v15, v124, v15
	v_add_f32_e32 v15, v125, v15
	v_cvt_pk_bf16_f32 v154, v124, v125
	ds_read_b64_tr_b16 v[2:3], v14 offset:54272
	ds_read_b64_tr_b16 v[4:5], v14 offset:54784
	s_waitcnt lgkmcnt(8)
	v_mfma_f32_32x32x16_bf16 v[80:95], v[136:139], v[144:147], v[80:95]
	v_add_f32_e32 v15, v126, v15
	v_add_f32_e32 v15, v127, v15
	v_cvt_pk_bf16_f32 v155, v126, v127
	s_nop 1
	v_max_f32_e32 v116, v97, v97
	v_max_f32_e32 v117, v96, v96
	v_max_f32_e32 v116, v117, v116
	s_nop 3
	v_max3_f32 v117, v98, v99, v81
	v_max3_f32 v116, v116, v80, v82
	v_max3_f32 v116, v116, v83, v100
	v_max3_f32 v117, v117, v102, v103
	v_max3_f32 v116, v116, v101, v84
	v_max3_f32 v117, v117, v86, v87
	v_max3_f32 v116, v116, v85, v104
	v_max3_f32 v117, v117, v106, v107
	v_max3_f32 v116, v116, v105, v88
	v_max3_f32 v117, v117, v90, v91
	v_max3_f32 v116, v116, v89, v108
	v_max3_f32 v117, v117, v110, v111
	v_max3_f32 v116, v116, v109, v92
	v_max3_f32 v117, v117, v94, v95
	v_add_f32_e32 v218, v0, v15
	v_max3_f32 v0, v116, v93, v117
	v_mov_b32_e32 v15, v0
	s_nop 1
	v_permlane32_swap_b32_e32 v0, v15
	v_max_f32_e32 v15, v15, v15
	v_max_f32_e32 v0, v0, v0
	v_max_f32_e32 v0, v0, v15
	v_cmp_lt_f32_e32 vcc, s94, v0
	s_cmp_lg_u64 vcc, 0
	s_cselect_b64 s[62:63], -1, 0
	s_cbranch_vccnz .LBB0_843

.LBB0_849:
	s_add_i32 s72, s95, -2
	s_and_b32 s10, s72, 3
	s_mulk_i32 s10, 0x3000
	v_add_u32_e32 v152, s10, v214
	ds_read_b128 v[2:5], v152 offset:4096
	v_add_u32_e32 v246, s23, v217
	s_waitcnt lgkmcnt(4)
	v_mfma_f32_32x32x16_bf16 v[128:143], v[196:199], v[176:179], v[64:79]
	v_add_f32_e32 v6, v96, v97
	v_add_f32_e32 v6, v98, v6
	v_add_f32_e32 v6, v99, v6
	v_add_f32_e32 v10, v100, v6
	v_cvt_pk_bf16_f32 v180, v96, v97
	ds_read_b128 v[6:9], v152 offset:4608
	s_waitcnt lgkmcnt(4)
	v_mfma_f32_32x32x16_bf16 v[112:127], v[184:187], v[176:179], v[64:79]
	v_add_f32_e32 v10, v101, v10
	v_add_f32_e32 v10, v102, v10
	v_add_f32_e32 v96, v103, v10
	v_cvt_pk_bf16_f32 v181, v98, v99
	ds_read_b128 v[10:13], v152 offset:6144
	s_waitcnt lgkmcnt(4)
	v_mfma_f32_32x32x16_bf16 v[128:143], v[188:191], v[168:171], v[128:143]
	v_add_f32_e32 v96, v104, v96
	v_add_f32_e32 v96, v105, v96
	v_add_f32_e32 v153, v106, v96
	v_cvt_pk_bf16_f32 v182, v100, v101
	ds_read_b128 v[96:99], v152 offset:6656
	s_waitcnt lgkmcnt(4)
	v_mfma_f32_32x32x16_bf16 v[112:127], v[192:195], v[168:171], v[112:127]
	v_add_f32_e32 v100, v107, v153
	v_add_f32_e32 v100, v108, v100
	v_add_f32_e32 v153, v109, v100
	v_cvt_pk_bf16_f32 v183, v102, v103
	ds_read_b128 v[100:103], v152 offset:8192
	s_waitcnt lgkmcnt(4)
	v_mfma_f32_32x32x16_bf16 v[128:143], v[2:5], v[164:167], v[128:143]
	v_add_f32_e32 v153, v110, v153
	v_add_f32_e32 v153, v111, v153
	v_add_f32_e32 v153, v80, v153
	v_cvt_pk_bf16_f32 v172, v104, v105
	ds_read_b128 v[2:5], v152 offset:8704
	s_waitcnt lgkmcnt(4)
	v_mfma_f32_32x32x16_bf16 v[112:127], v[6:9], v[164:167], v[112:127]
	v_add_f32_e32 v104, v81, v153
	v_add_f32_e32 v104, v82, v104
	v_add_f32_e32 v153, v83, v104
	v_cvt_pk_bf16_f32 v173, v106, v107
	ds_read_b128 v[104:107], v152 offset:10240
	s_waitcnt lgkmcnt(4)
	v_mfma_f32_32x32x16_bf16 v[128:143], v[10:13], v[156:159], v[128:143]
	v_add_f32_e32 v6, v84, v153
	v_add_f32_e32 v6, v85, v6
	v_cvt_pk_bf16_f32 v174, v108, v109
	v_cvt_pk_bf16_f32 v175, v110, v111
	ds_read_b128 v[108:111], v152 offset:10752
	s_waitcnt lgkmcnt(4)
	v_mfma_f32_32x32x16_bf16 v[112:127], v[96:99], v[156:159], v[112:127]
	v_add_f32_e32 v6, v86, v6
	v_add_f32_e32 v6, v87, v6
	v_cvt_pk_bf16_f32 v160, v80, v81
	v_cvt_pk_bf16_f32 v161, v82, v83
	ds_read_b64_tr_b16 v[80:81], v246 offset:49152
	ds_read_b64_tr_b16 v[82:83], v246 offset:49664
	s_waitcnt lgkmcnt(5)
	v_mfma_f32_32x32x16_bf16 v[128:143], v[100:103], v[148:151], v[128:143]
	v_add_f32_e32 v6, v88, v6
	v_add_f32_e32 v6, v89, v6
	v_cvt_pk_bf16_f32 v162, v84, v85
	v_cvt_pk_bf16_f32 v163, v86, v87
	ds_read_b64_tr_b16 v[10:11], v246 offset:53248
	ds_read_b64_tr_b16 v[12:13], v246 offset:53760
	s_waitcnt lgkmcnt(6)
	v_mfma_f32_32x32x16_bf16 v[112:127], v[2:5], v[148:151], v[112:127]
	v_add_f32_e32 v6, v90, v6
	v_add_f32_e32 v84, v91, v6
	v_cvt_pk_bf16_f32 v152, v88, v89
	v_cvt_pk_bf16_f32 v153, v90, v91
	ds_read_b64_tr_b16 v[6:7], v246 offset:50176
	ds_read_b64_tr_b16 v[8:9], v246 offset:50688
	s_waitcnt lgkmcnt(7)
	v_mfma_f32_32x32x16_bf16 v[128:143], v[104:107], v[144:147], v[128:143]
	v_add_f32_e32 v2, v92, v84
	v_add_f32_e32 v84, v93, v2
	v_cvt_pk_bf16_f32 v154, v92, v93
	ds_read_b64_tr_b16 v[2:3], v246 offset:54272
	ds_read_b64_tr_b16 v[4:5], v246 offset:54784
	s_waitcnt lgkmcnt(8)
	v_mfma_f32_32x32x16_bf16 v[112:127], v[108:111], v[144:147], v[112:127]
	v_add_f32_e32 v84, v94, v84
	v_add_f32_e32 v84, v95, v84
	v_cvt_pk_bf16_f32 v155, v94, v95
	s_add_i32 s6, s95, 1
	s_cmp_ge_u32 s6, s1
	s_cselect_b64 s[66:67], -1, 0
	s_and_b64 vcc, exec, s[66:67]
	s_cbranch_vccnz .LBB0_851
	s_add_u32 s7, s62, s58
	s_addc_u32 s23, s63, s59
	s_add_u32 s68, s7, 0x30000
	s_addc_u32 s69, s23, 0
	s_and_b32 s6, s6, 3
	s_mul_i32 s23, s6, 0x3000
	s_add_i32 s6, s23, s78
	s_mov_b32 m0, s6
	s_nop 0
	global_load_lds_dwordx4 v216, s[68:69]
	s_add_u32 s6, s60, 0xfffff000
	s_addc_u32 s7, s61, -1
	s_add_i32 s23, s23, s85
	s_mov_b32 m0, s23
	s_nop 0
	global_load_lds_dwordx4 v216, s[6:7]
.LBB0_851:
	s_add_u32 s23, s64, s58
	s_addc_u32 s70, s65, s59
	s_add_u32 s6, s23, 0x10000
	s_addc_u32 s7, s70, 0
	s_add_i32 s71, s13, s95
	s_add_i32 s68, s22, s86
	s_add_i32 s69, s71, 2
	s_cmp_lt_i32 s69, 0
	s_mov_b32 m0, s68
	s_nop 0
	global_load_lds_dwordx4 v216, s[6:7]
	s_cbranch_scc1 .LBB0_853
	v_subrev_u32_e32 v85, 64, v245
	v_cmp_le_i32_e32 vcc, v85, v14
	v_subrev_u32_e32 v86, 62, v245
	s_nop 0
	v_cndmask_b32_e32 v112, v203, v112, vcc
	v_cmp_lt_i32_e32 vcc, v85, v213
	s_nop 1
	v_cndmask_b32_e32 v129, v203, v129, vcc
	v_cmp_le_i32_e32 vcc, v85, v213
	s_nop 1
	v_cndmask_b32_e32 v128, v203, v128, vcc
	v_cmp_le_i32_e32 vcc, v85, v15
	s_nop 1
	v_cndmask_b32_e32 v113, v203, v113, vcc
	v_cmp_le_i32_e32 vcc, v86, v213
	v_subrev_u32_e32 v86, 61, v245
	s_nop 0
	v_cndmask_b32_e32 v130, v203, v130, vcc
	v_cmp_le_i32_e32 vcc, v85, v219
	s_nop 1
	v_cndmask_b32_e32 v114, v203, v114, vcc
	v_cmp_le_i32_e32 vcc, v86, v213
	s_nop 1
	v_cndmask_b32_e32 v131, v203, v131, vcc
	v_cmp_le_i32_e32 vcc, v85, v220
	s_nop 1
	v_cndmask_b32_e32 v115, v203, v115, vcc
	v_cmp_le_i32_e32 vcc, v85, v221
	s_nop 1
	v_cndmask_b32_e32 v132, v203, v132, vcc
	v_cmp_le_i32_e32 vcc, v85, v222
	s_nop 1
	v_cndmask_b32_e32 v116, v203, v116, vcc
	v_cmp_le_i32_e32 vcc, v85, v223
	s_nop 1
	v_cndmask_b32_e32 v133, v203, v133, vcc
	v_cmp_le_i32_e32 vcc, v85, v224
	s_nop 1
	v_cndmask_b32_e32 v117, v203, v117, vcc
	v_cmp_le_i32_e32 vcc, v85, v225
	s_nop 1
	v_cndmask_b32_e32 v134, v203, v134, vcc
	v_cmp_le_i32_e32 vcc, v85, v226
	s_nop 1
	v_cndmask_b32_e32 v118, v203, v118, vcc
	v_cmp_le_i32_e32 vcc, v85, v227
	s_nop 1
	v_cndmask_b32_e32 v135, v203, v135, vcc
	v_cmp_le_i32_e32 vcc, v85, v228
	s_nop 1
	v_cndmask_b32_e32 v119, v203, v119, vcc
	v_cmp_le_i32_e32 vcc, v85, v229
	s_nop 1
	v_cndmask_b32_e32 v136, v203, v136, vcc
	v_cmp_le_i32_e32 vcc, v85, v230
	s_nop 1
	v_cndmask_b32_e32 v120, v203, v120, vcc
	v_cmp_le_i32_e32 vcc, v85, v231
	s_nop 1
	v_cndmask_b32_e32 v137, v203, v137, vcc
	v_cmp_le_i32_e32 vcc, v85, v232
	s_nop 1
	v_cndmask_b32_e32 v121, v203, v121, vcc
	v_cmp_le_i32_e32 vcc, v85, v233
	s_nop 1
	v_cndmask_b32_e32 v138, v203, v138, vcc
	v_cmp_le_i32_e32 vcc, v85, v234
	s_nop 1
	v_cndmask_b32_e32 v122, v203, v122, vcc
	v_cmp_le_i32_e32 vcc, v85, v235
	s_nop 1
	v_cndmask_b32_e32 v139, v203, v139, vcc
	v_cmp_le_i32_e32 vcc, v85, v236
	s_nop 1
	v_cndmask_b32_e32 v123, v203, v123, vcc
	v_cmp_le_i32_e32 vcc, v85, v237
	s_nop 1
	v_cndmask_b32_e32 v140, v203, v140, vcc
	v_cmp_le_i32_e32 vcc, v85, v238
	s_nop 1
	v_cndmask_b32_e32 v124, v203, v124, vcc
	v_cmp_le_i32_e32 vcc, v85, v239
	s_nop 1
	v_cndmask_b32_e32 v141, v203, v141, vcc
	v_cmp_le_i32_e32 vcc, v85, v240
	s_nop 1
	v_cndmask_b32_e32 v125, v203, v125, vcc
	v_cmp_le_i32_e32 vcc, v85, v241
	s_nop 1
	v_cndmask_b32_e32 v142, v203, v142, vcc
	v_cmp_le_i32_e32 vcc, v85, v242
	s_nop 1
	v_cndmask_b32_e32 v126, v203, v126, vcc
	v_cmp_le_i32_e32 vcc, v85, v243
	s_nop 1
	v_cndmask_b32_e32 v143, v203, v143, vcc
	v_cmp_le_i32_e32 vcc, v85, v244
	s_nop 1
	v_cndmask_b32_e32 v127, v203, v127, vcc

.LBB0_858:
	ds_read_b128 v[4:7], v2 offset:4096
	v_add_u32_e32 v246, s12, v217
	s_waitcnt lgkmcnt(4)
	v_mfma_f32_32x32x16_bf16 v[96:111], v[196:199], v[176:179], v[64:79]
	v_add_f32_e32 v3, v128, v129
	v_add_f32_e32 v3, v130, v3
	v_add_f32_e32 v3, v131, v3
	v_add_f32_e32 v3, v132, v3
	v_cvt_pk_bf16_f32 v180, v128, v129
	ds_read_b128 v[8:11], v2 offset:4608
	s_waitcnt lgkmcnt(4)
	v_mfma_f32_32x32x16_bf16 v[80:95], v[184:187], v[176:179], v[64:79]
	v_add_f32_e32 v3, v133, v3
	v_add_f32_e32 v3, v134, v3
	v_add_f32_e32 v3, v135, v3
	v_cvt_pk_bf16_f32 v181, v130, v131
	ds_read_b128 v[128:131], v2 offset:6144
	s_waitcnt lgkmcnt(4)
	v_mfma_f32_32x32x16_bf16 v[96:111], v[188:191], v[168:171], v[96:111]
	v_add_f32_e32 v3, v136, v3
	v_add_f32_e32 v3, v137, v3
	v_add_f32_e32 v3, v138, v3
	v_cvt_pk_bf16_f32 v182, v132, v133
	ds_read_b128 v[248:251], v2 offset:6656
	s_waitcnt lgkmcnt(4)
	v_mfma_f32_32x32x16_bf16 v[80:95], v[192:195], v[168:171], v[80:95]
	v_add_f32_e32 v3, v139, v3
	v_add_f32_e32 v3, v140, v3
	v_add_f32_e32 v3, v141, v3
	v_cvt_pk_bf16_f32 v183, v134, v135
	ds_read_b128 v[132:135], v2 offset:8192
	s_waitcnt lgkmcnt(4)
	v_mfma_f32_32x32x16_bf16 v[96:111], v[4:7], v[164:167], v[96:111]
	v_add_f32_e32 v3, v142, v3
	v_add_f32_e32 v3, v143, v3
	v_add_f32_e32 v3, v112, v3
	v_cvt_pk_bf16_f32 v172, v136, v137
	ds_read_b128 v[4:7], v2 offset:8704
	s_waitcnt lgkmcnt(4)
	v_mfma_f32_32x32x16_bf16 v[80:95], v[8:11], v[164:167], v[80:95]
	v_add_f32_e32 v3, v113, v3
	v_add_f32_e32 v3, v114, v3
	v_add_f32_e32 v3, v115, v3
	v_cvt_pk_bf16_f32 v173, v138, v139
	ds_read_b128 v[136:139], v2 offset:10240
	s_waitcnt lgkmcnt(4)
	v_mfma_f32_32x32x16_bf16 v[96:111], v[128:131], v[156:159], v[96:111]
	v_add_f32_e32 v3, v116, v3
	v_add_f32_e32 v3, v117, v3
	v_cvt_pk_bf16_f32 v174, v140, v141
	v_cvt_pk_bf16_f32 v175, v142, v143
	ds_read_b128 v[128:131], v2 offset:10752
	s_waitcnt lgkmcnt(4)
	v_mfma_f32_32x32x16_bf16 v[80:95], v[248:251], v[156:159], v[80:95]
	v_add_f32_e32 v2, v118, v3
	v_add_f32_e32 v2, v119, v2
	v_cvt_pk_bf16_f32 v160, v112, v113
	v_cvt_pk_bf16_f32 v161, v114, v115
	ds_read_b64_tr_b16 v[112:113], v246 offset:49152
	ds_read_b64_tr_b16 v[114:115], v246 offset:49664
	s_waitcnt lgkmcnt(5)
	v_mfma_f32_32x32x16_bf16 v[96:111], v[132:135], v[148:151], v[96:111]
	v_add_f32_e32 v2, v120, v2
	v_add_f32_e32 v2, v121, v2
	v_cvt_pk_bf16_f32 v162, v116, v117
	v_cvt_pk_bf16_f32 v163, v118, v119
	ds_read_b64_tr_b16 v[10:11], v246 offset:53248
	ds_read_b64_tr_b16 v[12:13], v246 offset:53760
	s_waitcnt lgkmcnt(6)
	v_mfma_f32_32x32x16_bf16 v[80:95], v[4:7], v[148:151], v[80:95]
	v_add_f32_e32 v2, v122, v2
	v_add_f32_e32 v2, v123, v2
	v_cvt_pk_bf16_f32 v152, v120, v121
	v_cvt_pk_bf16_f32 v153, v122, v123
	ds_read_b64_tr_b16 v[6:7], v246 offset:50176
	ds_read_b64_tr_b16 v[8:9], v246 offset:50688
	s_waitcnt lgkmcnt(7)
	v_mfma_f32_32x32x16_bf16 v[96:111], v[136:139], v[144:147], v[96:111]
	v_add_f32_e32 v2, v124, v2
	v_add_f32_e32 v116, v125, v2
	v_cvt_pk_bf16_f32 v154, v124, v125
	ds_read_b64_tr_b16 v[2:3], v246 offset:54272
	ds_read_b64_tr_b16 v[4:5], v246 offset:54784
	s_waitcnt lgkmcnt(8)
	v_mfma_f32_32x32x16_bf16 v[80:95], v[128:131], v[144:147], v[80:95]
	v_add_f32_e32 v116, v126, v116
	v_add_f32_e32 v116, v127, v116
	v_cvt_pk_bf16_f32 v155, v126, v127
	s_add_i32 s96, s95, 2
	s_cmp_ge_u32 s96, s1
	s_cselect_b64 s[68:69], -1, 0
	s_and_b64 vcc, exec, s[68:69]
	s_cbranch_vccnz .LBB0_860
	s_add_u32 s6, s62, s58
	s_addc_u32 s7, s63, s59
	s_add_u32 s6, s6, 0x40000
	s_addc_u32 s7, s7, 0
	s_add_i32 s12, s10, s78
	s_mov_b32 m0, s12
	s_nop 0
	global_load_lds_dwordx4 v216, s[6:7]
	s_add_i32 s10, s10, s85
	s_mov_b32 m0, s10
	s_nop 0
	global_load_lds_dwordx4 v216, s[60:61]
.LBB0_860:
	s_add_i32 s6, s22, 0x2000
	s_cmpk_lg_i32 s22, 0x4000
	s_cselect_b32 s12, s6, 0
	s_cmp_lt_u32 s95, s1
	s_cselect_b64 s[72:73], -1, 0
	s_cmp_ge_u32 s95, s1
	s_cbranch_scc1 .LBB0_862
	s_add_u32 s6, s23, 0x20000
	s_addc_u32 s7, s70, 0
	s_add_i32 s10, s12, s86
	s_mov_b32 m0, s10
	s_nop 0
	global_load_lds_dwordx4 v216, s[6:7]

.LBB0_898:
	s_add_i32 s1, s0, 1
	s_lshr_b32 s4, s1, 1
	s_add_i32 s6, s4, s3
	s_sub_i32 s7, 15, s6
	s_and_b64 s[4:5], s[56:57], exec
	s_cselect_b32 s4, s7, s6
	s_cmp_lg_u32 s0, 7
	s_cselect_b32 s0, s4, -1
	s_cmp_lt_i32 s0, 0
	s_cbranch_scc1 .LBB0_900
	s_mov_b32 m0, s78
	s_nop 0
	global_load_lds_dwordx4 v216, s[14:15]
	s_lshl_b32 s0, s0, 8
	s_mov_b32 m0, s85
	s_nop 0
	global_load_lds_dwordx4 v216, s[16:17]
	s_add_u32 s0, s75, s0
	s_addc_u32 s4, s79, 0
	s_mulk_i32 s4, 0x600
	s_mul_hi_u32 s5, s0, 0x600
	s_add_i32 s5, s5, s4
	s_mulk_i32 s0, 0x600
	s_add_u32 s4, s81, s0
	v_lshrrev_b32_e32 v0, 1, v204
	s_movk_i32 s0, 0x600
	s_addc_u32 s5, s82, s5
	v_mul_lo_u32 v0, v0, s0
	s_lshl_b32 s0, s76, 11
	s_add_i32 s0, s0, 0
	v_lshlrev_b32_e32 v2, 6, v204
	s_add_i32 s6, s0, 0x1a800
	v_and_or_b32 v0, v2, 64, v0
	s_mov_b32 m0, s6
	s_nop 0
	global_load_lds_dwordx4 v0, s[4:5]
	s_add_u32 s4, s4, 0x70
	s_addc_u32 s5, s5, 0
	s_add_i32 s0, s0, 0x1ac00
	s_mov_b32 m0, s0
	s_nop 0
	global_load_lds_dwordx4 v0, s[4:5]
